# gated-residual GEMM epilogues: gate, norm-gain and norm-scale vectors loaded in one round instead of four serial rounds
# speedup vs baseline: 1.0009x; 1.0009x over previous
; __device__ __forceinline__ unsigned pkbf(float lo, float hi) { f32x2v v = {lo, hi}; bf16x2v b = __builtin_convertvector(v, bf16x2v); return __builtin_bit_cast(unsigned, b); }
; #define ER_LOAD(g) do { const bf16_t* xp_ = X + (size_t)(u.pm * BM + ((g) >> 2) * HALF + wr * 64 + ((g) & 3) * 16 + fr) * 2048 + hc; \
;         _Pragma("unroll") for (int bj = 0; bj < 2; ++bj) xr[(g) & 3][bj] = *(const u32x4*)(xp_ + bj * HALF); } while (0)
;     __device__ __forceinline__ void operator()(const f32x4 (&acc)[2][2][4][2], const Unit& u, int wr, int wc, int fr, int fq) const {
;     ...
;         const float* gate = modl + (size_t)bp * 12288 + goff;
;         f32x4 gv[2][2], gm[2][2];
; #pragma unroll
;         for (int bj = 0; bj < 2; ++bj)
; #pragma unroll
;             for (int n = 0; n < 2; ++n) { gv[bj][n] = *(const f32x4*)(gate + col0 + bj * HALF + n * 16);
;                 if (hx) { const f32x4 g4 = *(const f32x4*)(ng + col0 + bj * HALF + n * 16), s4 = *(const f32x4*)(nsc + (size_t)bp * 12288 + col0 + bj * HALF + n * 16); gm[bj][n] = g4 * (s4 + 1.f); } }
;         const int hc = u.pn * BM + wc * 32 + ((fq & 1) ? 16 + 4 * (fq - 1) : 4 * fq);
;         u32x4 xr[4][2]; float tots[4];
;     ...
;         ER_LOAD(0); ER_LOAD(1); ER_LOAD(2); ER_LOAD(3);
;         asm volatile("" ::: "memory");
; #pragma unroll
;         for (int g = 0; g < 8; ++g) { const int ai = g >> 2, m = g & 3; const int row = u.pm * BM + ai * HALF + wr * 64 + m * 16 + fr; float ss = 0.f;
; #pragma unroll
;             for (int bj = 0; bj < 2; ++bj) { const u32x4 raw = xr[g & 3][bj];
;                 const auto lx = __builtin_amdgcn_permlane16_swap(raw[0], raw[2], false, false); const auto ly = __builtin_amdgcn_permlane16_swap(raw[1], raw[3], false, false);
;                 unsigned xw[2][2], hw[2][2];
; #pragma unroll
;                 for (int n = 0; n < 2; ++n) { const unsigned wx = lx[n], wy = ly[n];
;                     f32x4 xv = {__uint_as_float(wx << 16), __uint_as_float(wx & 0xffff0000u), __uint_as_float(wy << 16), __uint_as_float(wy & 0xffff0000u)};
;                     xv = xv + gv[bj][n] * acc[ai][bj][m][n]; xw[n][0] = pkbf(xv[0], xv[1]); xw[n][1] = pkbf(xv[2], xv[3]);
;                     if (hx) { ss += (xv[0] * xv[0] + xv[1] * xv[1]) + (xv[2] * xv[2] + xv[3] * xv[3]); const f32x4 hv = xv * gm[bj][n]; hw[n][0] = pkbf(hv[0], hv[1]); hw[n][1] = pkbf(hv[2], hv[3]); } }
.LBB0_1071:
	s_mul_i32 s8, s9, 0xffffffdf
	s_sub_i32 s19, 0, s24
	s_cmp_lg_u32 s8, s19
	s_cselect_b32 s8, s9, 4
	s_mul_hi_i32 s19, s8, 0xc000
	s_mul_i32 s23, s8, 0xc000
	v_readlane_b32 s8, v254, 49
	v_readlane_b32 s9, v254, 50
	s_add_u32 s8, s8, s23
	s_addc_u32 s9, s9, s19
	v_lshlrev_b64 v[74:75], 2, v[34:35]
	v_lshl_add_u64 v[72:73], s[8:9], 0, v[74:75]
	s_add_u32 s8, s78, s23
	s_addc_u32 s9, s79, s19
	v_lshl_add_u64 v[34:35], s[10:11], 0, v[74:75]
	v_lshl_add_u64 v[152:153], s[8:9], 0, v[74:75]
	v_add_co_u32_e32 v74, vcc, 0x4000, v72
	v_cndmask_b32_e64 v32, 0, 1, s[48:49]
	s_nop 0
	v_addc_co_u32_e32 v75, vcc, 0, v73, vcc
	global_load_dwordx4 v[80:83], v[74:75], off
	v_cmp_ne_u32_e64 s[8:9], 1, v32
	s_mov_b64 s[26:27], 0x4000
	v_lshl_add_u64 v[72:73], v[72:73], 0, s[26:27]
	global_load_dwordx4 v[88:91], v[72:73], off offset:64
	global_load_dwordx4 v[76:79], v[72:73], off offset:512
	s_andn2_b64 vcc, exec, s[48:49]
	s_cbranch_vccnz .Lepr_skipa
	global_load_dwordx4 v[154:157], v[152:153], off
	global_load_dwordx4 v[170:173], v[34:35], off
	global_load_dwordx4 v[158:161], v[152:153], off offset:64
	global_load_dwordx4 v[174:177], v[34:35], off offset:64
	global_load_dwordx4 v[162:165], v[152:153], off offset:512
	global_load_dwordx4 v[226:229], v[34:35], off offset:512
	global_load_dwordx4 v[166:169], v[152:153], off offset:576
	global_load_dwordx4 v[218:221], v[34:35], off offset:576
	global_load_dwordx4 v[72:75], v[72:73], off offset:576
	s_waitcnt vmcnt(0)
	v_pk_add_f32 v[156:157], v[156:157], 1.0 op_sel_hi:[1,0]
	v_pk_add_f32 v[154:155], v[154:155], 1.0 op_sel_hi:[1,0]
	v_pk_mul_f32 v[216:217], v[172:173], v[156:157]
	v_pk_mul_f32 v[214:215], v[170:171], v[154:155]
	v_pk_add_f32 v[160:161], v[160:161], 1.0 op_sel_hi:[1,0]
	v_pk_add_f32 v[158:159], v[158:159], 1.0 op_sel_hi:[1,0]
	v_pk_mul_f32 v[212:213], v[176:177], v[160:161]
	v_pk_mul_f32 v[210:211], v[174:175], v[158:159]
	v_pk_add_f32 v[164:165], v[164:165], 1.0 op_sel_hi:[1,0]
	v_pk_add_f32 v[162:163], v[162:163], 1.0 op_sel_hi:[1,0]
	v_pk_mul_f32 v[208:209], v[228:229], v[164:165]
	v_pk_mul_f32 v[206:207], v[226:227], v[162:163]
	v_pk_add_f32 v[168:169], v[168:169], 1.0 op_sel_hi:[1,0]
	v_pk_add_f32 v[166:167], v[166:167], 1.0 op_sel_hi:[1,0]
	v_pk_mul_f32 v[204:205], v[220:221], v[168:169]
	v_pk_mul_f32 v[202:203], v[218:219], v[166:167]
	s_branch .LBB0_1079
.Lepr_skipa:
	global_load_dwordx4 v[72:75], v[72:73], off offset:576
.LBB0_1079:
	v_or_b32_e32 v200, s17, v241
	s_lshl_b32 s17, s24, 8
	v_add_u32_e32 v218, s17, v182
	v_ashrrev_i32_e32 v219, 31, v218
	v_lshlrev_b64 v[34:35], 12, v[218:219]
	v_ashrrev_i32_e32 v201, 31, v200
	v_lshl_add_u64 v[34:35], s[72:73], 0, v[34:35]
	v_lshlrev_b64 v[152:153], 1, v[200:201]
	v_lshl_add_u64 v[224:225], v[34:35], 0, v[152:153]
	v_or_b32_e32 v34, 16, v218
	v_ashrrev_i32_e32 v35, 31, v34
	v_lshlrev_b64 v[34:35], 12, v[34:35]
	v_lshl_add_u64 v[34:35], s[72:73], 0, v[34:35]
	v_lshl_add_u64 v[222:223], v[34:35], 0, v[152:153]
	v_or_b32_e32 v34, 32, v218
	v_ashrrev_i32_e32 v35, 31, v34
	v_lshlrev_b64 v[34:35], 12, v[34:35]
	v_lshl_add_u64 v[34:35], s[72:73], 0, v[34:35]
	v_lshl_add_u64 v[220:221], v[34:35], 0, v[152:153]
	v_or_b32_e32 v34, 48, v218
	v_ashrrev_i32_e32 v35, 31, v34
	global_load_dwordx4 v[226:229], v[224:225], off
	global_load_dwordx4 v[176:179], v[224:225], off offset:256
	v_lshlrev_b64 v[34:35], 12, v[34:35]
	v_lshl_add_u64 v[34:35], s[72:73], 0, v[34:35]
	v_lshl_add_u64 v[34:35], v[34:35], 0, v[152:153]
	global_load_dwordx4 v[172:175], v[222:223], off
	global_load_dwordx4 v[168:171], v[222:223], off offset:256
	global_load_dwordx4 v[164:167], v[220:221], off
	global_load_dwordx4 v[160:163], v[220:221], off offset:256
	global_load_dwordx4 v[156:159], v[34:35], off
	global_load_dwordx4 v[152:155], v[34:35], off offset:256
	s_and_b64 vcc, exec, s[8:9]
	s_waitcnt vmcnt(0)
	v_mov_b32_e32 v191, v228
	v_mov_b32_e32 v190, v229
	s_nop 0
	v_permlane16_swap_b32_e32 v226, v191
	v_permlane16_swap_b32_e32 v227, v190
	v_lshlrev_b32_e32 v34, 16, v226
	v_and_b32_e32 v35, 0xffff0000, v226
	v_lshlrev_b32_e32 v186, 16, v227
	v_and_b32_e32 v187, 0xffff0000, v227
	v_pk_fma_f32 v[226:227], v[86:87], v[82:83], v[186:187]
	v_pk_fma_f32 v[228:229], v[84:85], v[80:81], v[34:35]
	s_cbranch_vccnz .LBB0_1081
	v_pk_mul_f32 v[34:35], v[226:227], v[226:227]
	v_pk_mul_f32 v[84:85], v[228:229], v[228:229]
	s_nop 0
	v_pk_mov_b32 v[86:87], v[84:85], v[34:35] op_sel:[1,0]
	v_mov_b32_e32 v85, v35
	v_pk_add_f32 v[34:35], v[86:87], v[84:85]
	v_pk_mul_f32 v[84:85], v[214:215], v[228:229]
	v_add_f32_e32 v230, v34, v35
	v_pk_mul_f32 v[34:35], v[216:217], v[226:227]
	v_cvt_pk_bf16_f32 v84, v84, v85
	v_cvt_pk_bf16_f32 v85, v34, v35
	v_mov_b32_e32 v86, v33
	v_mov_b32_e32 v87, v33
	s_branch .LBB0_1082

; __device__ __forceinline__ unsigned pkbf(float lo, float hi) { f32x2v v = {lo, hi}; bf16x2v b = __builtin_convertvector(v, bf16x2v); return __builtin_bit_cast(unsigned, b); }
; #define ER_LOAD(g) do { const bf16_t* xp_ = X + (size_t)(u.pm * BM + ((g) >> 2) * HALF + wr * 64 + ((g) & 3) * 16 + fr) * 2048 + hc; \
;         _Pragma("unroll") for (int bj = 0; bj < 2; ++bj) xr[(g) & 3][bj] = *(const u32x4*)(xp_ + bj * HALF); } while (0)
;     __device__ __forceinline__ void operator()(const f32x4 (&acc)[2][2][4][2], const Unit& u, int wr, int wc, int fr, int fq) const {
;     ...
;         const float* gate = modl + (size_t)bp * 12288 + goff;
;         f32x4 gv[2][2], gm[2][2];
; #pragma unroll
;         for (int bj = 0; bj < 2; ++bj)
; #pragma unroll
;             for (int n = 0; n < 2; ++n) { gv[bj][n] = *(const f32x4*)(gate + col0 + bj * HALF + n * 16);
;                 if (hx) { const f32x4 g4 = *(const f32x4*)(ng + col0 + bj * HALF + n * 16), s4 = *(const f32x4*)(nsc + (size_t)bp * 12288 + col0 + bj * HALF + n * 16); gm[bj][n] = g4 * (s4 + 1.f); } }
;         const int hc = u.pn * BM + wc * 32 + ((fq & 1) ? 16 + 4 * (fq - 1) : 4 * fq);
;         u32x4 xr[4][2]; float tots[4];
;     ...
;         ER_LOAD(0); ER_LOAD(1); ER_LOAD(2); ER_LOAD(3);
;         asm volatile("" ::: "memory");
; #pragma unroll
;         for (int g = 0; g < 8; ++g) { const int ai = g >> 2, m = g & 3; const int row = u.pm * BM + ai * HALF + wr * 64 + m * 16 + fr; float ss = 0.f;
; #pragma unroll
;             for (int bj = 0; bj < 2; ++bj) { const u32x4 raw = xr[g & 3][bj];
;                 const auto lx = __builtin_amdgcn_permlane16_swap(raw[0], raw[2], false, false); const auto ly = __builtin_amdgcn_permlane16_swap(raw[1], raw[3], false, false);
;                 unsigned xw[2][2], hw[2][2];
; #pragma unroll
;                 for (int n = 0; n < 2; ++n) { const unsigned wx = lx[n], wy = ly[n];
;                     f32x4 xv = {__uint_as_float(wx << 16), __uint_as_float(wx & 0xffff0000u), __uint_as_float(wy << 16), __uint_as_float(wy & 0xffff0000u)};
;                     xv = xv + gv[bj][n] * acc[ai][bj][m][n]; xw[n][0] = pkbf(xv[0], xv[1]); xw[n][1] = pkbf(xv[2], xv[3]);
;                     if (hx) { ss += (xv[0] * xv[0] + xv[1] * xv[1]) + (xv[2] * xv[2] + xv[3] * xv[3]); const f32x4 hv = xv * gm[bj][n]; hw[n][0] = pkbf(hv[0], hv[1]); hw[n][1] = pkbf(hv[2], hv[3]); } }
.LBB0_1461:
	s_mul_i32 s8, s9, 0xffffffdf
	s_sub_i32 s25, 0, s24
	s_cmp_lg_u32 s8, s25
	s_cselect_b32 s8, s9, 4
	s_mul_i32 s26, s8, 0xc000
	s_mul_hi_i32 s25, s8, 0xc000
	s_add_u32 s8, s48, s26
	s_addc_u32 s9, s49, s25
	v_lshlrev_b64 v[74:75], 2, v[34:35]
	v_lshl_add_u64 v[72:73], s[8:9], 0, v[74:75]
	s_add_u32 s8, s82, s26
	v_readlane_b32 s9, v254, 55
	s_addc_u32 s9, s9, s25
	v_lshl_add_u64 v[34:35], s[12:13], 0, v[74:75]
	v_lshl_add_u64 v[152:153], s[8:9], 0, v[74:75]
	v_add_co_u32_e32 v74, vcc, 0xa000, v72
	v_cndmask_b32_e64 v32, 0, 1, s[18:19]
	s_nop 0
	v_addc_co_u32_e32 v75, vcc, 0, v73, vcc
	global_load_dwordx4 v[80:83], v[74:75], off
	v_cmp_ne_u32_e64 s[8:9], 1, v32
	s_mov_b64 s[26:27], 0xa000
	v_lshl_add_u64 v[72:73], v[72:73], 0, s[26:27]
	global_load_dwordx4 v[88:91], v[72:73], off offset:64
	global_load_dwordx4 v[76:79], v[72:73], off offset:512
	s_andn2_b64 vcc, exec, s[18:19]
	s_cbranch_vccnz .Lepr_skipb
	global_load_dwordx4 v[154:157], v[152:153], off
	global_load_dwordx4 v[170:173], v[34:35], off
	global_load_dwordx4 v[158:161], v[152:153], off offset:64
	global_load_dwordx4 v[174:177], v[34:35], off offset:64
	global_load_dwordx4 v[162:165], v[152:153], off offset:512
	global_load_dwordx4 v[186:189], v[34:35], off offset:512
	global_load_dwordx4 v[166:169], v[152:153], off offset:576
	global_load_dwordx4 v[218:221], v[34:35], off offset:576
	global_load_dwordx4 v[72:75], v[72:73], off offset:576
	s_waitcnt vmcnt(0)
	v_pk_add_f32 v[156:157], v[156:157], 1.0 op_sel_hi:[1,0]
	v_pk_add_f32 v[154:155], v[154:155], 1.0 op_sel_hi:[1,0]
	v_pk_mul_f32 v[216:217], v[172:173], v[156:157]
	v_pk_mul_f32 v[214:215], v[170:171], v[154:155]
	v_pk_add_f32 v[160:161], v[160:161], 1.0 op_sel_hi:[1,0]
	v_pk_add_f32 v[158:159], v[158:159], 1.0 op_sel_hi:[1,0]
	v_pk_mul_f32 v[212:213], v[176:177], v[160:161]
	v_pk_mul_f32 v[210:211], v[174:175], v[158:159]
	v_pk_add_f32 v[164:165], v[164:165], 1.0 op_sel_hi:[1,0]
	v_pk_add_f32 v[162:163], v[162:163], 1.0 op_sel_hi:[1,0]
	v_pk_mul_f32 v[208:209], v[188:189], v[164:165]
	v_pk_mul_f32 v[206:207], v[186:187], v[162:163]
	v_pk_add_f32 v[168:169], v[168:169], 1.0 op_sel_hi:[1,0]
	v_pk_add_f32 v[166:167], v[166:167], 1.0 op_sel_hi:[1,0]
	v_pk_mul_f32 v[204:205], v[220:221], v[168:169]
	v_pk_mul_f32 v[202:203], v[218:219], v[166:167]
	s_branch .LBB0_1469
.Lepr_skipb:
	global_load_dwordx4 v[72:75], v[72:73], off offset:576
.LBB0_1469:
	v_or_b32_e32 v200, s23, v241
	s_lshl_b32 s23, s24, 8
	v_add_u32_e32 v218, s23, v182
	v_ashrrev_i32_e32 v219, 31, v218
	v_lshlrev_b64 v[34:35], 12, v[218:219]
	v_ashrrev_i32_e32 v201, 31, v200
	v_lshl_add_u64 v[34:35], s[72:73], 0, v[34:35]
	v_lshlrev_b64 v[152:153], 1, v[200:201]
	v_lshl_add_u64 v[224:225], v[34:35], 0, v[152:153]
	v_or_b32_e32 v34, 16, v218
	v_ashrrev_i32_e32 v35, 31, v34
	v_lshlrev_b64 v[34:35], 12, v[34:35]
	v_lshl_add_u64 v[34:35], s[72:73], 0, v[34:35]
	v_lshl_add_u64 v[222:223], v[34:35], 0, v[152:153]
	v_or_b32_e32 v34, 32, v218
	v_ashrrev_i32_e32 v35, 31, v34
	v_lshlrev_b64 v[34:35], 12, v[34:35]
	v_lshl_add_u64 v[34:35], s[72:73], 0, v[34:35]
	v_lshl_add_u64 v[220:221], v[34:35], 0, v[152:153]
	v_or_b32_e32 v34, 48, v218
	v_ashrrev_i32_e32 v35, 31, v34
	global_load_dwordx4 v[186:189], v[224:225], off
	global_load_dwordx4 v[176:179], v[224:225], off offset:256
	v_lshlrev_b64 v[34:35], 12, v[34:35]
	v_lshl_add_u64 v[34:35], s[72:73], 0, v[34:35]
	v_lshl_add_u64 v[34:35], v[34:35], 0, v[152:153]
	global_load_dwordx4 v[172:175], v[222:223], off
	global_load_dwordx4 v[168:171], v[222:223], off offset:256
	global_load_dwordx4 v[164:167], v[220:221], off
	global_load_dwordx4 v[160:163], v[220:221], off offset:256
	global_load_dwordx4 v[156:159], v[34:35], off
	global_load_dwordx4 v[152:155], v[34:35], off offset:256
	s_and_b64 vcc, exec, s[8:9]
	s_waitcnt vmcnt(0)
	v_mov_b32_e32 v191, v188
	v_mov_b32_e32 v190, v189
	s_nop 0
	v_permlane16_swap_b32_e32 v186, v191
	v_permlane16_swap_b32_e32 v187, v190
	v_lshlrev_b32_e32 v34, 16, v186
	v_and_b32_e32 v35, 0xffff0000, v186
	v_lshlrev_b32_e32 v186, 16, v187
	v_and_b32_e32 v187, 0xffff0000, v187
	v_pk_fma_f32 v[226:227], v[86:87], v[82:83], v[186:187]
	v_pk_fma_f32 v[228:229], v[84:85], v[80:81], v[34:35]
	s_cbranch_vccnz .LBB0_1471
	v_pk_mul_f32 v[34:35], v[226:227], v[226:227]
	v_pk_mul_f32 v[84:85], v[228:229], v[228:229]
	s_nop 0
	v_pk_mov_b32 v[86:87], v[84:85], v[34:35] op_sel:[1,0]
	v_mov_b32_e32 v85, v35
	v_pk_add_f32 v[34:35], v[86:87], v[84:85]
	v_pk_mul_f32 v[84:85], v[214:215], v[228:229]
	v_add_f32_e32 v230, v34, v35
	v_pk_mul_f32 v[34:35], v[216:217], v[226:227]
	v_cvt_pk_bf16_f32 v84, v84, v85
	v_cvt_pk_bf16_f32 v85, v34, v35
	v_mov_b32_e32 v86, v33
	v_mov_b32_e32 v87, v33
	s_branch .LBB0_1472
